# top-256 search: bootstrap probe three binades below the wave maximum before the log-space Illinois iterations
# speedup vs baseline: 1.0106x; 1.0106x over previous
; DI int wave_sum_i(int x) { x = row_sum16(x); return __builtin_amdgcn_readlane(x, 0) + __builtin_amdgcn_readlane(x, 16) + __builtin_amdgcn_readlane(x, 32) + __builtin_amdgcn_readlane(x, 48); }
; DI void index_unit(Frame& F, int b, int t0) {
;     ...
;         unsigned res = 0u;
;         const int nreg = (t >> 6) + 1;
; #pragma unroll 1
;     ...
;             const unsigned cand = res | (1u << bit);
;             int cl = 0;
; #pragma unroll
;             for (int gq = 0; gq < 8; ++gq) if (8 * gq < nreg) {
; #pragma unroll
;                 for (int i = 8 * gq; i < 8 * gq + 8; i += 4) cl = cnt4_ge(key[i], key[i + 1], key[i + 2], key[i + 3], cand, cl); }
;             const int cnt = wave_sum_i(cl);
;             if (cnt >= 256) { res = cand; if (cnt == 256) break; }
;         }
.Lsel_decide:
	s_add_i32 s101, s101, 1
	s_cmpk_eq_i32 s35, 0x100
	s_cbranch_scc1 .Lsel_found
	s_cmpk_gt_i32 s101, 48
	s_cbranch_scc1 .Lsel_fallback0
	s_cmp_eq_u32 s99, 1
	s_cbranch_scc0 .Lsel_m23
	s_cmpk_lt_i32 s35, 0x100
	s_cbranch_scc1 .Lsel_fallback
	v_cvt_f32_i32_e32 v210, s35
	v_max_f32_e32 v210, 0.5, v210
	v_log_f32_e32 v210, v210
	s_nop 0
	v_add_f32_e32 v210, 0xc1000000, v210
	v_add_u32_e32 v5, 0xfe800000, v213
	v_max_u32_e32 v5, 0x80000001, v5
	s_mov_b32 s99, 3
	s_branch .Lsel_count
.Lsel_m23:
	s_cmp_eq_u32 s99, 3
	s_cbranch_scc0 .Lsel_step
	v_cvt_f32_i32_e32 v214, s35
	v_max_f32_e32 v214, 0.5, v214
	v_log_f32_e32 v214, v214
	s_nop 0
	v_add_f32_e32 v214, 0xc1000000, v214
	s_mov_b32 s99, 2
	v_mov_b32_e32 v212, 0
	s_cmpk_gt_i32 s35, 0x100
	s_cbranch_scc0 .Lsel_m3lo
	v_mov_b32_e32 v208, v5
	v_mov_b32_e32 v210, v214
	v_add_u32_e32 v209, 1, v213
	v_mov_b32_e32 v211, 0xc1100000
	s_branch .Lsel_next
.Lsel_m3lo:
	v_bfrev_b32_e32 v208, 1
	v_mov_b32_e32 v209, v5
	v_mov_b32_e32 v211, v214
	s_branch .Lsel_next
